# adds: in-proj GEMM K-loop LDS-DMA loads addressed as SGPR base + 32-bit lane offset (no per-load VALU address arithmetic competing with the other wave's MFMA issue)
# speedup vs baseline: 1.0057x; 1.0057x over previous
; #define PG8_STAGE(bufoff, gbase, voff) do { unsigned _g = (gbase); asm volatile("" : "+s"(_g));   _Pragma("unroll") for (int _i = 0; _i < 2; ++_i) \
;         __builtin_amdgcn_global_load_lds((const unsigned*)(wsb + (size_t)(unsigned)(_g + (voff)[_i])), (LAS unsigned*)(lds + (bufoff) + ldsw + _i * 8192), 16, 0, 0); } while (0)
; #define PG8_WAIT_V(n) asm volatile("s_waitcnt vmcnt(" #n ")" ::: "memory")
; #define PG8_WAIT_L(n) asm volatile("s_waitcnt lgkmcnt(" #n ")" ::: "memory")
; #define PG8_BAR __builtin_amdgcn_s_barrier()
; #define PG8_SCHED __builtin_amdgcn_sched_barrier(0)
;     ...
;             const unsigned a1 = cA + (unsigned)(t + 1) * kstep;
;             const unsigned a2 = last ? nA : cA + (unsigned)(t + 2) * kstep, b2 = last ? nB : cB + (unsigned)(t + 2) * kstep;
;             const unsigned a3 = a2 + kstep, b3 = b2 + kstep;
;             if constexpr (SP2) {
;             PG8_LDB(B0, 0, 0); PG8_LDB(B1, 0, 1); PG8_SCHED; PG8_LDA(At, 0, 0); PG8_STAGE(PG8_SA(1, 1), a1 + hstep, voffA);
;             PG8_WAIT_V(8); PG8_WAIT_L(0); PG8_BAR; PG8_MMA(0, 0, At, B0); PG8_MMA(0, 1, At, B1); PG8_BAR; PG8_SCHED;
;             PG8_LDA(At, 0, 1); PG8_STAGE(PG8_SB(0, 0), b2, voffB); PG8_STAGE(PG8_SB(0, 1), b2 + hstep, voffB); PG8_STAGE(PG8_SA(0, 0), a2, voffA);
;             PG8_WAIT_V(8); PG8_WAIT_L(0); PG8_BAR; PG8_MMA(1, 0, At, B0); PG8_MMA(1, 1, At, B1); PG8_BAR; PG8_SCHED;
.LBB0_279:
	v_readfirstlane_b32 s100, v130
	v_readfirstlane_b32 s101, v131
	s_add_i32 s11, s8, 0xfff00080
	s_cmp_eq_u32 s10, 60
	s_cselect_b32 s83, s4, s11
	s_cselect_b32 s82, s5, s9
	s_add_i32 s84, 0, 0x10000
	v_add_u32_e32 v0, s84, v152
	s_add_i32 s96, 0, 0x14000
	ds_read_b128 v[138:141], v0
	ds_read_b128 v[142:145], v0 offset:1024
	ds_read_b128 v[154:157], v0 offset:2048
	ds_read_b128 v[158:161], v0 offset:3072
	v_add_u32_e32 v0, s96, v152
	ds_read_b128 v[162:165], v0
	ds_read_b128 v[166:169], v0 offset:1024
	ds_read_b128 v[170:173], v0 offset:2048
	ds_read_b128 v[174:177], v0 offset:3072
	s_add_i32 s11, s83, 0x80
	s_mov_b32 s97, s8
	ds_read_b128 v[178:181], v153
	ds_read_b128 v[182:185], v153 offset:1024
	ds_read_b128 v[186:189], v153 offset:2048
	ds_read_b128 v[190:193], v153 offset:3072
	ds_read_b128 v[194:197], v153 offset:4096
	ds_read_b128 v[198:201], v153 offset:5120
	ds_read_b128 v[202:205], v153 offset:6144
	ds_read_b128 v[206:209], v153 offset:7168
	s_cmp_eq_i32 s10, -2
	s_cbranch_scc1 .Lin_g0_first
.Lin_g0_norm:
	s_add_i32 m0, s38, 0xc000
	s_add_u32 vcc_lo, s100, s97
	s_addc_u32 vcc_hi, s101, 0
	global_load_lds_dwordx4 v148, vcc
	s_add_i32 m0, s38, 0xe000
	s_nop 0
	global_load_lds_dwordx4 v150, vcc
	s_waitcnt vmcnt(8)
.Lin_g0_join:
	s_waitcnt lgkmcnt(0)
	s_barrier
	s_setprio 1
	s_waitcnt lgkmcnt(0)
	v_mfma_f32_16x16x32_bf16 v[126:129], v[138:141], v[178:181], v[126:129]
	v_mfma_f32_16x16x32_bf16 v[122:125], v[154:157], v[178:181], v[122:125]
	v_mfma_f32_16x16x32_bf16 v[110:113], v[138:141], v[186:189], v[110:113]
	v_mfma_f32_16x16x32_bf16 v[106:109], v[154:157], v[186:189], v[106:109]
	v_mfma_f32_16x16x32_bf16 v[94:97], v[138:141], v[194:197], v[94:97]
	v_mfma_f32_16x16x32_bf16 v[90:93], v[154:157], v[194:197], v[90:93]
	v_mfma_f32_16x16x32_bf16 v[78:81], v[138:141], v[202:205], v[78:81]
	v_mfma_f32_16x16x32_bf16 v[74:77], v[154:157], v[202:205], v[74:77]
	v_mfma_f32_16x16x32_bf16 v[126:129], v[142:145], v[182:185], v[126:129]
	v_mfma_f32_16x16x32_bf16 v[122:125], v[158:161], v[182:185], v[122:125]
	v_mfma_f32_16x16x32_bf16 v[110:113], v[142:145], v[190:193], v[110:113]
	v_mfma_f32_16x16x32_bf16 v[106:109], v[158:161], v[190:193], v[106:109]
	v_mfma_f32_16x16x32_bf16 v[94:97], v[142:145], v[198:201], v[94:97]
	v_mfma_f32_16x16x32_bf16 v[90:93], v[158:161], v[198:201], v[90:93]
	v_mfma_f32_16x16x32_bf16 v[78:81], v[142:145], v[206:209], v[78:81]
	v_mfma_f32_16x16x32_bf16 v[74:77], v[158:161], v[206:209], v[74:77]
	s_setprio 0
	s_setprio 1
	v_mfma_f32_16x16x32_bf16 v[118:121], v[162:165], v[178:181], v[118:121]
	v_mfma_f32_16x16x32_bf16 v[114:117], v[170:173], v[178:181], v[114:117]
	v_mfma_f32_16x16x32_bf16 v[102:105], v[162:165], v[186:189], v[102:105]
	v_mfma_f32_16x16x32_bf16 v[98:101], v[170:173], v[186:189], v[98:101]
	v_mfma_f32_16x16x32_bf16 v[86:89], v[162:165], v[194:197], v[86:89]
	v_mfma_f32_16x16x32_bf16 v[82:85], v[170:173], v[194:197], v[82:85]
	v_mfma_f32_16x16x32_bf16 v[70:73], v[162:165], v[202:205], v[70:73]
	v_mfma_f32_16x16x32_bf16 v[66:69], v[170:173], v[202:205], v[66:69]
	v_mfma_f32_16x16x32_bf16 v[118:121], v[166:169], v[182:185], v[118:121]
	v_mfma_f32_16x16x32_bf16 v[114:117], v[174:177], v[182:185], v[114:117]
	v_mfma_f32_16x16x32_bf16 v[102:105], v[166:169], v[190:193], v[102:105]
	v_mfma_f32_16x16x32_bf16 v[98:101], v[174:177], v[190:193], v[98:101]
	v_mfma_f32_16x16x32_bf16 v[86:89], v[166:169], v[198:201], v[86:89]
	v_mfma_f32_16x16x32_bf16 v[82:85], v[174:177], v[198:201], v[82:85]
	v_mfma_f32_16x16x32_bf16 v[70:73], v[166:169], v[206:209], v[70:73]
	v_mfma_f32_16x16x32_bf16 v[66:69], v[174:177], v[206:209], v[66:69]
	s_setprio 0
	s_barrier
	s_mov_b32 s97, s82
	ds_read_b128 v[178:181], v153 offset:16384
	ds_read_b128 v[182:185], v153 offset:17408
	ds_read_b128 v[186:189], v153 offset:18432
	ds_read_b128 v[190:193], v153 offset:19456
	ds_read_b128 v[194:197], v153 offset:20480
	ds_read_b128 v[198:201], v153 offset:21504
	ds_read_b128 v[202:205], v153 offset:22528
	ds_read_b128 v[206:209], v153 offset:23552
	s_add_i32 s84, s84, s7
	s_add_u32 vcc_lo, s100, s97
	s_addc_u32 vcc_hi, s101, 0
	s_mov_b32 m0, s84
	s_nop 0
	global_load_lds_dwordx4 v149, vcc
	s_add_i32 m0, s84, 0x2000
	s_add_i32 s84, s82, 0x100000
	global_load_lds_dwordx4 v151, vcc
	s_add_i32 s96, s96, s7
	s_add_u32 vcc_lo, s100, s84
	s_addc_u32 vcc_hi, s101, 0
	s_mov_b32 m0, s96
	s_nop 0
	global_load_lds_dwordx4 v149, vcc
	s_add_i32 m0, s96, 0x2000
	s_mov_b32 s84, s83
	global_load_lds_dwordx4 v151, vcc
	s_mov_b32 m0, s38
	s_add_u32 vcc_lo, s100, s84
	s_addc_u32 vcc_hi, s101, 0
	global_load_lds_dwordx4 v148, vcc
	s_mov_b32 m0, s39
	s_nop 0
	global_load_lds_dwordx4 v150, vcc
	s_cmp_eq_i32 s10, -2
	s_cbranch_scc1 .Lin_g1_first

; #define PG8_STAGE(bufoff, gbase, voff) do { unsigned _g = (gbase); asm volatile("" : "+s"(_g));   _Pragma("unroll") for (int _i = 0; _i < 2; ++_i) \
;         __builtin_amdgcn_global_load_lds((const unsigned*)(wsb + (size_t)(unsigned)(_g + (voff)[_i])), (LAS unsigned*)(lds + (bufoff) + ldsw + _i * 8192), 16, 0, 0); } while (0)
; #define PG8_WAIT_V(n) asm volatile("s_waitcnt vmcnt(" #n ")" ::: "memory")
; #define PG8_WAIT_L(n) asm volatile("s_waitcnt lgkmcnt(" #n ")" ::: "memory")
; #define PG8_BAR __builtin_amdgcn_s_barrier()
; #define PG8_SCHED __builtin_amdgcn_sched_barrier(0)
;     ...
;             PG8_WAIT_V(8); PG8_WAIT_L(0); PG8_BAR; PG8_MMA(1, 0, At, B0); PG8_MMA(1, 1, At, B1); PG8_BAR; PG8_SCHED;
;             PG8_LDB(B0, 1, 0); PG8_LDB(B1, 1, 1); PG8_SCHED; PG8_LDA(At, 1, 0); PG8_STAGE(PG8_SA(0, 1), a2 + hstep, voffA);
.Lin_g1_join:
	s_waitcnt lgkmcnt(0)
	s_barrier
	s_setprio 1
	s_waitcnt lgkmcnt(0)
	v_mfma_f32_16x16x32_bf16 v[62:65], v[138:141], v[178:181], v[62:65]
	v_mfma_f32_16x16x32_bf16 v[58:61], v[154:157], v[178:181], v[58:61]
	v_mfma_f32_16x16x32_bf16 v[46:49], v[138:141], v[186:189], v[46:49]
	v_mfma_f32_16x16x32_bf16 v[42:45], v[154:157], v[186:189], v[42:45]
	v_mfma_f32_16x16x32_bf16 v[30:33], v[138:141], v[194:197], v[30:33]
	v_mfma_f32_16x16x32_bf16 v[26:29], v[154:157], v[194:197], v[26:29]
	v_mfma_f32_16x16x32_bf16 v[14:17], v[138:141], v[202:205], v[14:17]
	v_mfma_f32_16x16x32_bf16 v[10:13], v[154:157], v[202:205], v[10:13]
	v_mfma_f32_16x16x32_bf16 v[62:65], v[142:145], v[182:185], v[62:65]
	v_mfma_f32_16x16x32_bf16 v[58:61], v[158:161], v[182:185], v[58:61]
	v_mfma_f32_16x16x32_bf16 v[46:49], v[142:145], v[190:193], v[46:49]
	v_mfma_f32_16x16x32_bf16 v[42:45], v[158:161], v[190:193], v[42:45]
	v_mfma_f32_16x16x32_bf16 v[30:33], v[142:145], v[198:201], v[30:33]
	v_mfma_f32_16x16x32_bf16 v[26:29], v[158:161], v[198:201], v[26:29]
	v_mfma_f32_16x16x32_bf16 v[14:17], v[142:145], v[206:209], v[14:17]
	v_mfma_f32_16x16x32_bf16 v[10:13], v[158:161], v[206:209], v[10:13]
	s_setprio 0
	s_setprio 1
	v_mfma_f32_16x16x32_bf16 v[54:57], v[162:165], v[178:181], v[54:57]
	v_mfma_f32_16x16x32_bf16 v[50:53], v[170:173], v[178:181], v[50:53]
	v_mfma_f32_16x16x32_bf16 v[38:41], v[162:165], v[186:189], v[38:41]
	v_mfma_f32_16x16x32_bf16 v[34:37], v[170:173], v[186:189], v[34:37]
	v_mfma_f32_16x16x32_bf16 v[22:25], v[162:165], v[194:197], v[22:25]
	v_mfma_f32_16x16x32_bf16 v[18:21], v[170:173], v[194:197], v[18:21]
	v_mfma_f32_16x16x32_bf16 v[6:9], v[162:165], v[202:205], v[6:9]
	v_mfma_f32_16x16x32_bf16 v[2:5], v[170:173], v[202:205], v[2:5]
	v_mfma_f32_16x16x32_bf16 v[54:57], v[166:169], v[182:185], v[54:57]
	v_mfma_f32_16x16x32_bf16 v[50:53], v[174:177], v[182:185], v[50:53]
	v_mfma_f32_16x16x32_bf16 v[38:41], v[166:169], v[190:193], v[38:41]
	v_mfma_f32_16x16x32_bf16 v[34:37], v[174:177], v[190:193], v[34:37]
	v_mfma_f32_16x16x32_bf16 v[22:25], v[166:169], v[198:201], v[22:25]
	v_mfma_f32_16x16x32_bf16 v[18:21], v[174:177], v[198:201], v[18:21]
	v_mfma_f32_16x16x32_bf16 v[6:9], v[166:169], v[206:209], v[6:9]
	v_mfma_f32_16x16x32_bf16 v[2:5], v[174:177], v[206:209], v[2:5]
	s_setprio 0
	s_barrier
	s_add_i32 s84, 0, 0x18000
	v_add_u32_e32 v0, s84, v152
	s_add_i32 s96, 0, 0x1c000
	ds_read_b128 v[138:141], v0
	ds_read_b128 v[142:145], v0 offset:1024
	ds_read_b128 v[154:157], v0 offset:2048
	ds_read_b128 v[158:161], v0 offset:3072
	v_add_u32_e32 v0, s96, v152
	ds_read_b128 v[162:165], v0
	ds_read_b128 v[166:169], v0 offset:1024
	ds_read_b128 v[170:173], v0 offset:2048
	ds_read_b128 v[174:177], v0 offset:3072
	s_add_i32 s83, s83, 0x100000
	ds_read_b128 v[178:181], v153 offset:32768
	ds_read_b128 v[182:185], v153 offset:33792
	ds_read_b128 v[186:189], v153 offset:34816
	ds_read_b128 v[190:193], v153 offset:35840
	ds_read_b128 v[194:197], v153 offset:36864
	ds_read_b128 v[198:201], v153 offset:37888
	ds_read_b128 v[202:205], v153 offset:38912
	ds_read_b128 v[206:209], v153 offset:39936
	s_mov_b32 m0, s44
	s_add_u32 vcc_lo, s100, s83
	s_addc_u32 vcc_hi, s101, 0
	global_load_lds_dwordx4 v148, vcc
	s_mov_b32 m0, s45
	s_nop 0
	global_load_lds_dwordx4 v150, vcc
	s_cmp_eq_i32 s10, -2
	s_cbranch_scc1 .Lin_g2_first

; #define PG8_STAGE(bufoff, gbase, voff) do { unsigned _g = (gbase); asm volatile("" : "+s"(_g));   _Pragma("unroll") for (int _i = 0; _i < 2; ++_i) \
;         __builtin_amdgcn_global_load_lds((const unsigned*)(wsb + (size_t)(unsigned)(_g + (voff)[_i])), (LAS unsigned*)(lds + (bufoff) + ldsw + _i * 8192), 16, 0, 0); } while (0)
; #define PG8_WAIT_V(n) asm volatile("s_waitcnt vmcnt(" #n ")" ::: "memory")
; #define PG8_WAIT_L(n) asm volatile("s_waitcnt lgkmcnt(" #n ")" ::: "memory")
; #define PG8_BAR __builtin_amdgcn_s_barrier()
; #define PG8_SCHED __builtin_amdgcn_sched_barrier(0)
;     ...
;             PG8_WAIT_V(8); PG8_WAIT_L(0); PG8_BAR; PG8_MMA(0, 0, At, B0); PG8_MMA(0, 1, At, B1); PG8_BAR; PG8_SCHED;
;             PG8_LDA(At, 1, 1); PG8_STAGE(PG8_SB(1, 0), b3, voffB); PG8_STAGE(PG8_SB(1, 1), b3 + hstep, voffB); PG8_STAGE(PG8_SA(1, 0), a3, voffA);
;             PG8_WAIT_V(8); PG8_WAIT_L(0); PG8_BAR; PG8_MMA(1, 0, At, B0); PG8_MMA(1, 1, At, B1); PG8_BAR; PG8_SCHED;
.Lin_g2_join:
	s_waitcnt lgkmcnt(0)
	s_barrier
	s_setprio 1
	s_waitcnt lgkmcnt(0)
	v_mfma_f32_16x16x32_bf16 v[126:129], v[138:141], v[178:181], v[126:129]
	v_mfma_f32_16x16x32_bf16 v[122:125], v[154:157], v[178:181], v[122:125]
	v_mfma_f32_16x16x32_bf16 v[110:113], v[138:141], v[186:189], v[110:113]
	v_mfma_f32_16x16x32_bf16 v[106:109], v[154:157], v[186:189], v[106:109]
	v_mfma_f32_16x16x32_bf16 v[94:97], v[138:141], v[194:197], v[94:97]
	v_mfma_f32_16x16x32_bf16 v[90:93], v[154:157], v[194:197], v[90:93]
	v_mfma_f32_16x16x32_bf16 v[78:81], v[138:141], v[202:205], v[78:81]
	v_mfma_f32_16x16x32_bf16 v[74:77], v[154:157], v[202:205], v[74:77]
	v_mfma_f32_16x16x32_bf16 v[126:129], v[142:145], v[182:185], v[126:129]
	v_mfma_f32_16x16x32_bf16 v[122:125], v[158:161], v[182:185], v[122:125]
	v_mfma_f32_16x16x32_bf16 v[110:113], v[142:145], v[190:193], v[110:113]
	v_mfma_f32_16x16x32_bf16 v[106:109], v[158:161], v[190:193], v[106:109]
	v_mfma_f32_16x16x32_bf16 v[94:97], v[142:145], v[198:201], v[94:97]
	v_mfma_f32_16x16x32_bf16 v[90:93], v[158:161], v[198:201], v[90:93]
	v_mfma_f32_16x16x32_bf16 v[78:81], v[142:145], v[206:209], v[78:81]
	v_mfma_f32_16x16x32_bf16 v[74:77], v[158:161], v[206:209], v[74:77]
	s_setprio 0
	s_setprio 1
	v_mfma_f32_16x16x32_bf16 v[118:121], v[162:165], v[178:181], v[118:121]
	v_mfma_f32_16x16x32_bf16 v[114:117], v[170:173], v[178:181], v[114:117]
	v_mfma_f32_16x16x32_bf16 v[102:105], v[162:165], v[186:189], v[102:105]
	v_mfma_f32_16x16x32_bf16 v[98:101], v[170:173], v[186:189], v[98:101]
	v_mfma_f32_16x16x32_bf16 v[86:89], v[162:165], v[194:197], v[86:89]
	v_mfma_f32_16x16x32_bf16 v[82:85], v[170:173], v[194:197], v[82:85]
	v_mfma_f32_16x16x32_bf16 v[70:73], v[162:165], v[202:205], v[70:73]
	v_mfma_f32_16x16x32_bf16 v[66:69], v[170:173], v[202:205], v[66:69]
	v_mfma_f32_16x16x32_bf16 v[118:121], v[166:169], v[182:185], v[118:121]
	v_mfma_f32_16x16x32_bf16 v[114:117], v[174:177], v[182:185], v[114:117]
	v_mfma_f32_16x16x32_bf16 v[102:105], v[166:169], v[190:193], v[102:105]
	v_mfma_f32_16x16x32_bf16 v[98:101], v[174:177], v[190:193], v[98:101]
	v_mfma_f32_16x16x32_bf16 v[86:89], v[166:169], v[198:201], v[86:89]
	v_mfma_f32_16x16x32_bf16 v[82:85], v[174:177], v[198:201], v[82:85]
	v_mfma_f32_16x16x32_bf16 v[70:73], v[166:169], v[206:209], v[70:73]
	v_mfma_f32_16x16x32_bf16 v[66:69], v[174:177], v[206:209], v[66:69]
	s_setprio 0
	s_barrier
	s_add_i32 s83, s82, 0x80
	ds_read_b128 v[178:181], v153 offset:49152
	ds_read_b128 v[182:185], v153 offset:50176
	ds_read_b128 v[186:189], v153 offset:51200
	ds_read_b128 v[190:193], v153 offset:52224
	ds_read_b128 v[194:197], v153 offset:53248
	ds_read_b128 v[198:201], v153 offset:54272
	ds_read_b128 v[202:205], v153 offset:55296
	ds_read_b128 v[206:209], v153 offset:56320
	s_add_i32 s84, s84, s7
	s_add_u32 vcc_lo, s100, s83
	s_addc_u32 vcc_hi, s101, 0
	s_mov_b32 m0, s84
	s_nop 0
	global_load_lds_dwordx4 v149, vcc
	s_add_i32 m0, s84, 0x2000
	s_add_i32 s82, s82, 0x100080
	global_load_lds_dwordx4 v151, vcc
	s_add_i32 s83, s96, s7
	s_add_u32 vcc_lo, s100, s82
	s_addc_u32 vcc_hi, s101, 0
	s_mov_b32 m0, s83
	s_nop 0
	global_load_lds_dwordx4 v149, vcc
	s_add_i32 m0, s83, 0x2000
	s_nop 0
	global_load_lds_dwordx4 v151, vcc
	s_mov_b32 m0, s46
	s_add_u32 vcc_lo, s100, s11
	s_addc_u32 vcc_hi, s101, 0
	global_load_lds_dwordx4 v148, vcc
	s_mov_b32 m0, s47
	s_nop 0
	global_load_lds_dwordx4 v150, vcc
	s_waitcnt vmcnt(8)
	s_waitcnt lgkmcnt(0)
	s_barrier
	s_setprio 1
	s_waitcnt lgkmcnt(0)
	v_mfma_f32_16x16x32_bf16 v[62:65], v[138:141], v[178:181], v[62:65]
	v_mfma_f32_16x16x32_bf16 v[58:61], v[154:157], v[178:181], v[58:61]
	v_mfma_f32_16x16x32_bf16 v[46:49], v[138:141], v[186:189], v[46:49]
	v_mfma_f32_16x16x32_bf16 v[42:45], v[154:157], v[186:189], v[42:45]
	v_mfma_f32_16x16x32_bf16 v[30:33], v[138:141], v[194:197], v[30:33]
	v_mfma_f32_16x16x32_bf16 v[26:29], v[154:157], v[194:197], v[26:29]
	v_mfma_f32_16x16x32_bf16 v[14:17], v[138:141], v[202:205], v[14:17]
	v_mfma_f32_16x16x32_bf16 v[10:13], v[154:157], v[202:205], v[10:13]
	v_mfma_f32_16x16x32_bf16 v[62:65], v[142:145], v[182:185], v[62:65]
	v_mfma_f32_16x16x32_bf16 v[58:61], v[158:161], v[182:185], v[58:61]
	v_mfma_f32_16x16x32_bf16 v[46:49], v[142:145], v[190:193], v[46:49]
	v_mfma_f32_16x16x32_bf16 v[42:45], v[158:161], v[190:193], v[42:45]
	v_mfma_f32_16x16x32_bf16 v[30:33], v[142:145], v[198:201], v[30:33]
	v_mfma_f32_16x16x32_bf16 v[26:29], v[158:161], v[198:201], v[26:29]
	v_mfma_f32_16x16x32_bf16 v[14:17], v[142:145], v[206:209], v[14:17]
	v_mfma_f32_16x16x32_bf16 v[10:13], v[158:161], v[206:209], v[10:13]
	s_setprio 0
	s_setprio 1
	v_mfma_f32_16x16x32_bf16 v[54:57], v[162:165], v[178:181], v[54:57]
	v_mfma_f32_16x16x32_bf16 v[50:53], v[170:173], v[178:181], v[50:53]
	v_mfma_f32_16x16x32_bf16 v[38:41], v[162:165], v[186:189], v[38:41]
	v_mfma_f32_16x16x32_bf16 v[34:37], v[170:173], v[186:189], v[34:37]
	v_mfma_f32_16x16x32_bf16 v[22:25], v[162:165], v[194:197], v[22:25]
	v_mfma_f32_16x16x32_bf16 v[18:21], v[170:173], v[194:197], v[18:21]
	v_mfma_f32_16x16x32_bf16 v[6:9], v[162:165], v[202:205], v[6:9]
	v_mfma_f32_16x16x32_bf16 v[2:5], v[170:173], v[202:205], v[2:5]
	v_mfma_f32_16x16x32_bf16 v[54:57], v[166:169], v[182:185], v[54:57]
	v_mfma_f32_16x16x32_bf16 v[50:53], v[174:177], v[182:185], v[50:53]
	v_mfma_f32_16x16x32_bf16 v[38:41], v[166:169], v[190:193], v[38:41]
	v_mfma_f32_16x16x32_bf16 v[34:37], v[174:177], v[190:193], v[34:37]
	v_mfma_f32_16x16x32_bf16 v[22:25], v[166:169], v[198:201], v[22:25]
	v_mfma_f32_16x16x32_bf16 v[18:21], v[174:177], v[198:201], v[18:21]
	v_mfma_f32_16x16x32_bf16 v[6:9], v[166:169], v[206:209], v[6:9]
	v_mfma_f32_16x16x32_bf16 v[2:5], v[174:177], v[206:209], v[2:5]
	s_setprio 0
	s_barrier
	s_add_i32 s10, s10, 2
	s_addk_i32 s8, 0x100
	s_addk_i32 s9, 0x100
	s_cmp_gt_u32 s10, 61
	s_cbranch_scc0 .LBB0_279
	s_mov_b64 s[10:11], -1
	s_mov_b64 s[4:5], 0
	s_cmp_lt_i32 s18, 1
	s_mov_b64 s[8:9], 0
	v_mbcnt_lo_u32_b32 v0, -1, 0
	v_mbcnt_hi_u32_b32 v0, -1, v0
	s_cbranch_scc1 .LBB0_295
	s_cmp_lg_u32 s18, 1
	s_cselect_b64 s[8:9], -1, 0
	s_cbranch_execz .LBB0_296

; #define LAS __attribute__((address_space(3)))
; __device__ __forceinline__ int lane_id_hw() { int l; asm volatile("v_mbcnt_lo_u32_b32 %0, -1, 0\n\tv_mbcnt_hi_u32_b32 %0, -1, %0" : "=v"(l)); return l; }
; __global__ void __launch_bounds__(NWAVES * 64, 2) fwd(Args args) {
;     extern __shared__ __attribute__((aligned(16))) unsigned char lds_raw[];
;     LAS unsigned char* lds = (LAS unsigned char*)lds_raw;
;     const int wave_s = __builtin_amdgcn_readfirstlane((int)threadIdx.x >> 6);
;     for (int u = wave_s * 64 + lane_id_hw(); u < (LDS_BYTES - LDSCTL_OFF) / 4; u += NWAVES * 64) ((LAS unsigned*)(lds + LDSCTL_OFF))[u] = 0u;
;     __syncthreads();
;     unsigned* const barw = (unsigned*)(args.ws + WS_CTL) + CW_BAR;
;     XcdBarrier bar; bar.bar = barw; bar.x = 0; bar.st = nullptr;
;     if (MK_ONE_LAUNCH) bar = xcd_barrier_post(barw, (volatile LAS unsigned*)(lds + MISC_OFF) + 8, wave_s == 0 && lane_id_hw() == 0);
	.amdhsa_kernel _Z3fwd4Args
		.amdhsa_group_segment_fixed_size 0
		.amdhsa_private_segment_fixed_size 0
		.amdhsa_kernarg_size 416
		.amdhsa_user_sgpr_count 2
		.amdhsa_user_sgpr_dispatch_ptr 0
		.amdhsa_user_sgpr_queue_ptr 0
		.amdhsa_user_sgpr_kernarg_segment_ptr 1
		.amdhsa_user_sgpr_dispatch_id 0
		.amdhsa_user_sgpr_kernarg_preload_length 0
		.amdhsa_user_sgpr_kernarg_preload_offset 0
		.amdhsa_user_sgpr_private_segment_size 0
		.amdhsa_uses_dynamic_stack 0
		.amdhsa_enable_private_segment 0
		.amdhsa_system_sgpr_workgroup_id_x 1
		.amdhsa_system_sgpr_workgroup_id_y 0
		.amdhsa_system_sgpr_workgroup_id_z 0
		.amdhsa_system_sgpr_workgroup_info 0
		.amdhsa_system_vgpr_workitem_id 0
		.amdhsa_next_free_vgpr 256
		.amdhsa_next_free_sgpr 102
		.amdhsa_accum_offset 256
		.amdhsa_reserve_vcc 1
		.amdhsa_float_round_mode_32 0
		.amdhsa_float_round_mode_16_64 0
		.amdhsa_float_denorm_mode_32 3
		.amdhsa_float_denorm_mode_16_64 3
		.amdhsa_dx10_clamp 1
		.amdhsa_ieee_mode 1
		.amdhsa_fp16_overflow 0
		.amdhsa_tg_split 0
		.amdhsa_exception_fp_ieee_invalid_op 0
		.amdhsa_exception_fp_denorm_src 0
		.amdhsa_exception_fp_ieee_div_zero 0
		.amdhsa_exception_fp_ieee_overflow 0
		.amdhsa_exception_fp_ieee_underflow 0
		.amdhsa_exception_fp_ieee_inexact 0
		.amdhsa_exception_int_div_zero 0
	.end_amdhsa_kernel

; #define LAS __attribute__((address_space(3)))
; __global__ void __launch_bounds__(NWAVES * 64, 2) fwd(Args args) {
;     extern __shared__ __attribute__((aligned(16))) unsigned char lds_raw[];
;     LAS unsigned char* lds = (LAS unsigned char*)lds_raw;
;     const int wave_s = __builtin_amdgcn_readfirstlane((int)threadIdx.x >> 6);
amdhsa.kernels:
  - .agpr_count:     0
    .args:
      - .offset:         0
        .size:           160
        .value_kind:     by_value
      - .offset:         160
        .size:           4
        .value_kind:     hidden_block_count_x
      - .offset:         164
        .size:           4
        .value_kind:     hidden_block_count_y
      - .offset:         168
        .size:           4
        .value_kind:     hidden_block_count_z
      - .offset:         172
        .size:           2
        .value_kind:     hidden_group_size_x
      - .offset:         174
        .size:           2
        .value_kind:     hidden_group_size_y
      - .offset:         176
        .size:           2
        .value_kind:     hidden_group_size_z
      - .offset:         178
        .size:           2
        .value_kind:     hidden_remainder_x
      - .offset:         180
        .size:           2
        .value_kind:     hidden_remainder_y
      - .offset:         182
        .size:           2
        .value_kind:     hidden_remainder_z
      - .offset:         200
        .size:           8
        .value_kind:     hidden_global_offset_x
      - .offset:         208
        .size:           8
        .value_kind:     hidden_global_offset_y
      - .offset:         216
        .size:           8
        .value_kind:     hidden_global_offset_z
      - .offset:         224
        .size:           2
        .value_kind:     hidden_grid_dims
      - .offset:         280
        .size:           4
        .value_kind:     hidden_dynamic_lds_size
    .group_segment_fixed_size: 0
    .kernarg_segment_align: 8
    .kernarg_segment_size: 416
    .language:       OpenCL C
    .language_version:
      - 2
      - 0
    .max_flat_workgroup_size: 512
    .name:           _Z3fwd4Args
    .private_segment_fixed_size: 0
    .sgpr_count:     108
    .sgpr_spill_count: 117
    .symbol:         _Z3fwd4Args.kd
    .uniform_work_group_size: 1
    .uses_dynamic_stack: false
    .vgpr_count:     256
    .vgpr_spill_count: 0
    .wavefront_size: 64
